# select: radix digit search inside the owning lane done in registers (monotone prefix count) instead of a 32-iteration LDS loop
# speedup vs baseline: 1.0105x; 1.0046x over previous
.Lsel_pass_end:
	s_waitcnt lgkmcnt(0)
	ds_read_b128 v[242:245], v83
	ds_read_b128 v[246:249], v83 offset:16
	ds_read_b128 v[250:253], v83 offset:32
	ds_read_b128 v[210:213], v83 offset:48
	v_cmp_ne_u32_e64 s[16:17], 63, v91
	s_waitcnt lgkmcnt(3)
	v_add_u32_e32 v90, v243, v242
	v_add3_u32 v90, v90, v244, v245
	s_waitcnt lgkmcnt(2)
	v_add3_u32 v90, v90, v246, v247
	v_add3_u32 v90, v90, v248, v249
	s_waitcnt lgkmcnt(1)
	v_add3_u32 v90, v90, v250, v251
	ds_read_b128 v[242:245], v83 offset:64
	v_add3_u32 v90, v90, v252, v253
	s_waitcnt lgkmcnt(1)
	v_add3_u32 v90, v90, v210, v211
	v_add3_u32 v90, v90, v212, v213
	ds_read_b128 v[210:213], v83 offset:80
	ds_read_b128 v[246:249], v83 offset:96
	s_waitcnt lgkmcnt(2)
	v_add3_u32 v90, v90, v242, v243
	v_add3_u32 v90, v90, v244, v245
	ds_read_b128 v[242:245], v83 offset:112
	s_waitcnt lgkmcnt(2)
	v_add3_u32 v90, v90, v210, v211
	v_add3_u32 v90, v90, v212, v213
	s_waitcnt lgkmcnt(1)
	v_add3_u32 v90, v90, v246, v247
	v_add3_u32 v90, v90, v248, v249
	s_waitcnt lgkmcnt(0)
	v_add3_u32 v90, v90, v242, v243
	v_addc_co_u32_e64 v210, s[16:17], 0, v215, s[16:17]
	v_add3_u32 v90, v90, v244, v245
	v_lshlrev_b32_e32 v210, 2, v210
	ds_bpermute_b32 v210, v210, v90
	v_cmp_gt_u32_e64 s[16:17], 62, v91
	s_waitcnt lgkmcnt(0)
	v_cndmask_b32_e64 v210, v210, 0, s[4:5]
	v_cndmask_b32_e64 v211, 0, 2, s[16:17]
	v_add_u32_e32 v210, v210, v90
	v_add_lshl_u32 v211, v211, v215, 2
	ds_bpermute_b32 v211, v211, v210
	v_cmp_gt_u32_e64 s[16:17], 60, v91
	s_waitcnt lgkmcnt(0)
	v_cndmask_b32_e64 v211, 0, v211, s[6:7]
	v_add_u32_e32 v210, v211, v210
	v_cndmask_b32_e64 v211, 0, 4, s[16:17]
	v_add_lshl_u32 v211, v211, v215, 2
	ds_bpermute_b32 v211, v211, v210
	v_cmp_gt_u32_e64 s[16:17], 56, v91
	s_waitcnt lgkmcnt(0)
	v_cndmask_b32_e64 v211, 0, v211, s[8:9]
	v_add_u32_e32 v210, v211, v210
	v_cndmask_b32_e64 v211, 0, 8, s[16:17]
	v_add_lshl_u32 v211, v211, v215, 2
	ds_bpermute_b32 v211, v211, v210
	v_cmp_gt_u32_e64 s[16:17], 48, v91
	s_waitcnt lgkmcnt(0)
	v_cndmask_b32_e64 v211, 0, v211, s[10:11]
	v_cndmask_b32_e64 v91, 0, 16, s[16:17]
	v_add_u32_e32 v210, v211, v210
	v_add_lshl_u32 v91, v91, v215, 2
	ds_bpermute_b32 v91, v91, v210
	s_waitcnt lgkmcnt(0)
	v_cndmask_b32_e64 v91, 0, v91, s[12:13]
	v_add_u32_e32 v91, v91, v210
	v_lshl_or_b32 v210, v215, 2, v219
	ds_bpermute_b32 v210, v210, v91
	s_waitcnt lgkmcnt(0)
	v_cndmask_b32_e64 v210, 0, v210, s[14:15]
	v_add_u32_e32 v91, v210, v91
	v_sub_u32_e32 v244, v91, v90
	v_cmp_lt_i32_e64 s[16:17], v244, v240
	v_cmp_ge_i32_e64 s[18:19], v91, v240
	s_and_b64 s[2:3], s[18:19], s[16:17]
	v_mov_b32_e32 v91, 0
	v_mov_b32_e32 v90, 0
	s_and_saveexec_b64 s[18:19], s[2:3]
	s_cbranch_execz .LBB0_676
	ds_read_b128 v[246:249], v83 offset:112
	ds_read_b128 v[250:253], v83 offset:96
	v_mov_b32_e32 v241, 0
	v_mov_b32_e32 v90, v244
	v_bfrev_b32_e32 v91, -2
	v_mov_b32_e32 v242, v244
	v_bfrev_b32_e32 v244, -2
	ds_read_b128 v[210:213], v83 offset:80
	s_waitcnt lgkmcnt(2)
	v_add_u32_e32 v243, v242, v249
	v_cmp_lt_i32_e64 s[16:17], v243, v240
	v_add_u32_e32 v242, v243, v248
	v_cmp_lt_i32_e64 s[22:23], v242, v240
	v_addc_co_u32_e64 v241, s[26:27], 0, v241, s[16:17]
	v_cndmask_b32_e64 v90, v90, v243, s[16:17]
	v_cndmask_b32_e64 v245, v243, v244, s[16:17]
	v_min_i32_e32 v91, v91, v245
	v_add_u32_e32 v243, v242, v247
	v_cmp_lt_i32_e64 s[16:17], v243, v240
	v_addc_co_u32_e64 v241, s[26:27], 0, v241, s[22:23]
	v_cndmask_b32_e64 v90, v90, v242, s[22:23]
	v_cndmask_b32_e64 v245, v242, v244, s[22:23]
	v_min_i32_e32 v91, v91, v245
	v_add_u32_e32 v242, v243, v246
	v_cmp_lt_i32_e64 s[22:23], v242, v240
	v_addc_co_u32_e64 v241, s[26:27], 0, v241, s[16:17]
	v_cndmask_b32_e64 v90, v90, v243, s[16:17]
	v_cndmask_b32_e64 v245, v243, v244, s[16:17]
	v_min_i32_e32 v91, v91, v245
	ds_read_b128 v[246:249], v83 offset:64
	s_waitcnt lgkmcnt(2)
	v_add_u32_e32 v243, v242, v253
	v_cmp_lt_i32_e64 s[16:17], v243, v240
	v_addc_co_u32_e64 v241, s[26:27], 0, v241, s[22:23]
	v_cndmask_b32_e64 v90, v90, v242, s[22:23]
	v_cndmask_b32_e64 v245, v242, v244, s[22:23]
	v_min_i32_e32 v91, v91, v245
	v_add_u32_e32 v242, v243, v252
	v_cmp_lt_i32_e64 s[22:23], v242, v240
	v_addc_co_u32_e64 v241, s[26:27], 0, v241, s[16:17]
	v_cndmask_b32_e64 v90, v90, v243, s[16:17]
	v_cndmask_b32_e64 v245, v243, v244, s[16:17]
	v_min_i32_e32 v91, v91, v245
	v_add_u32_e32 v243, v242, v251
	v_cmp_lt_i32_e64 s[16:17], v243, v240
	v_addc_co_u32_e64 v241, s[26:27], 0, v241, s[22:23]
	v_cndmask_b32_e64 v90, v90, v242, s[22:23]
	v_cndmask_b32_e64 v245, v242, v244, s[22:23]
	v_min_i32_e32 v91, v91, v245
	v_add_u32_e32 v242, v243, v250
	v_cmp_lt_i32_e64 s[22:23], v242, v240
	v_addc_co_u32_e64 v241, s[26:27], 0, v241, s[16:17]
	v_cndmask_b32_e64 v90, v90, v243, s[16:17]
	v_cndmask_b32_e64 v245, v243, v244, s[16:17]
	v_min_i32_e32 v91, v91, v245
	ds_read_b128 v[250:253], v83 offset:48
	s_waitcnt lgkmcnt(2)
	v_add_u32_e32 v243, v242, v213
	v_cmp_lt_i32_e64 s[16:17], v243, v240
	v_addc_co_u32_e64 v241, s[26:27], 0, v241, s[22:23]
	v_cndmask_b32_e64 v90, v90, v242, s[22:23]
	v_cndmask_b32_e64 v245, v242, v244, s[22:23]
	v_min_i32_e32 v91, v91, v245
	v_add_u32_e32 v242, v243, v212
	v_cmp_lt_i32_e64 s[22:23], v242, v240
	v_addc_co_u32_e64 v241, s[26:27], 0, v241, s[16:17]
	v_cndmask_b32_e64 v90, v90, v243, s[16:17]
	v_cndmask_b32_e64 v245, v243, v244, s[16:17]
	v_min_i32_e32 v91, v91, v245
	v_add_u32_e32 v243, v242, v211
	v_cmp_lt_i32_e64 s[16:17], v243, v240
	v_addc_co_u32_e64 v241, s[26:27], 0, v241, s[22:23]
	v_cndmask_b32_e64 v90, v90, v242, s[22:23]
	v_cndmask_b32_e64 v245, v242, v244, s[22:23]
	v_min_i32_e32 v91, v91, v245
	v_add_u32_e32 v242, v243, v210
	v_cmp_lt_i32_e64 s[22:23], v242, v240
	v_addc_co_u32_e64 v241, s[26:27], 0, v241, s[16:17]
	v_cndmask_b32_e64 v90, v90, v243, s[16:17]
	v_cndmask_b32_e64 v245, v243, v244, s[16:17]
	v_min_i32_e32 v91, v91, v245
	ds_read_b128 v[210:213], v83 offset:32
	s_waitcnt lgkmcnt(2)
	v_add_u32_e32 v243, v242, v249
	v_cmp_lt_i32_e64 s[16:17], v243, v240
	v_addc_co_u32_e64 v241, s[26:27], 0, v241, s[22:23]
	v_cndmask_b32_e64 v90, v90, v242, s[22:23]
	v_cndmask_b32_e64 v245, v242, v244, s[22:23]
	v_min_i32_e32 v91, v91, v245
	v_add_u32_e32 v242, v243, v248
	v_cmp_lt_i32_e64 s[22:23], v242, v240
	v_addc_co_u32_e64 v241, s[26:27], 0, v241, s[16:17]
	v_cndmask_b32_e64 v90, v90, v243, s[16:17]
	v_cndmask_b32_e64 v245, v243, v244, s[16:17]
	v_min_i32_e32 v91, v91, v245
	v_add_u32_e32 v243, v242, v247
	v_cmp_lt_i32_e64 s[16:17], v243, v240
	v_addc_co_u32_e64 v241, s[26:27], 0, v241, s[22:23]
	v_cndmask_b32_e64 v90, v90, v242, s[22:23]
	v_cndmask_b32_e64 v245, v242, v244, s[22:23]
	v_min_i32_e32 v91, v91, v245
	v_add_u32_e32 v242, v243, v246
	v_cmp_lt_i32_e64 s[22:23], v242, v240
	v_addc_co_u32_e64 v241, s[26:27], 0, v241, s[16:17]
	v_cndmask_b32_e64 v90, v90, v243, s[16:17]
	v_cndmask_b32_e64 v245, v243, v244, s[16:17]
	v_min_i32_e32 v91, v91, v245
	ds_read_b128 v[246:249], v83 offset:16
	s_waitcnt lgkmcnt(2)
	v_add_u32_e32 v243, v242, v253
	v_cmp_lt_i32_e64 s[16:17], v243, v240
	v_addc_co_u32_e64 v241, s[26:27], 0, v241, s[22:23]
	v_cndmask_b32_e64 v90, v90, v242, s[22:23]
	v_cndmask_b32_e64 v245, v242, v244, s[22:23]
	v_min_i32_e32 v91, v91, v245
	v_add_u32_e32 v242, v243, v252
	v_cmp_lt_i32_e64 s[22:23], v242, v240
	v_addc_co_u32_e64 v241, s[26:27], 0, v241, s[16:17]
	v_cndmask_b32_e64 v90, v90, v243, s[16:17]
	v_cndmask_b32_e64 v245, v243, v244, s[16:17]
	v_min_i32_e32 v91, v91, v245
	v_add_u32_e32 v243, v242, v251
	v_cmp_lt_i32_e64 s[16:17], v243, v240
	v_addc_co_u32_e64 v241, s[26:27], 0, v241, s[22:23]
	v_cndmask_b32_e64 v90, v90, v242, s[22:23]
	v_cndmask_b32_e64 v245, v242, v244, s[22:23]
	v_min_i32_e32 v91, v91, v245
	v_add_u32_e32 v242, v243, v250
	v_cmp_lt_i32_e64 s[22:23], v242, v240
	v_addc_co_u32_e64 v241, s[26:27], 0, v241, s[16:17]
	v_cndmask_b32_e64 v90, v90, v243, s[16:17]
	v_cndmask_b32_e64 v245, v243, v244, s[16:17]
	v_min_i32_e32 v91, v91, v245
	ds_read_b128 v[250:253], v83
	s_waitcnt lgkmcnt(2)
	v_add_u32_e32 v243, v242, v213
	v_cmp_lt_i32_e64 s[16:17], v243, v240
	v_addc_co_u32_e64 v241, s[26:27], 0, v241, s[22:23]
	v_cndmask_b32_e64 v90, v90, v242, s[22:23]
	v_cndmask_b32_e64 v245, v242, v244, s[22:23]
	v_min_i32_e32 v91, v91, v245
	v_add_u32_e32 v242, v243, v212
	v_cmp_lt_i32_e64 s[22:23], v242, v240
	v_addc_co_u32_e64 v241, s[26:27], 0, v241, s[16:17]
	v_cndmask_b32_e64 v90, v90, v243, s[16:17]
	v_cndmask_b32_e64 v245, v243, v244, s[16:17]
	v_min_i32_e32 v91, v91, v245
	v_add_u32_e32 v243, v242, v211
	v_cmp_lt_i32_e64 s[16:17], v243, v240
	v_addc_co_u32_e64 v241, s[26:27], 0, v241, s[22:23]
	v_cndmask_b32_e64 v90, v90, v242, s[22:23]
	v_cndmask_b32_e64 v245, v242, v244, s[22:23]
	v_min_i32_e32 v91, v91, v245
	v_add_u32_e32 v242, v243, v210
	v_cmp_lt_i32_e64 s[22:23], v242, v240
	v_addc_co_u32_e64 v241, s[26:27], 0, v241, s[16:17]
	v_cndmask_b32_e64 v90, v90, v243, s[16:17]
	v_cndmask_b32_e64 v245, v243, v244, s[16:17]
	v_min_i32_e32 v91, v91, v245
	s_waitcnt lgkmcnt(1)
	v_add_u32_e32 v243, v242, v249
	v_cmp_lt_i32_e64 s[16:17], v243, v240
	v_addc_co_u32_e64 v241, s[26:27], 0, v241, s[22:23]
	v_cndmask_b32_e64 v90, v90, v242, s[22:23]
	v_cndmask_b32_e64 v245, v242, v244, s[22:23]
	v_min_i32_e32 v91, v91, v245
	v_add_u32_e32 v242, v243, v248
	v_cmp_lt_i32_e64 s[22:23], v242, v240
	v_addc_co_u32_e64 v241, s[26:27], 0, v241, s[16:17]
	v_cndmask_b32_e64 v90, v90, v243, s[16:17]
	v_cndmask_b32_e64 v245, v243, v244, s[16:17]
	v_min_i32_e32 v91, v91, v245
	v_add_u32_e32 v243, v242, v247
	v_cmp_lt_i32_e64 s[16:17], v243, v240
	v_addc_co_u32_e64 v241, s[26:27], 0, v241, s[22:23]
	v_cndmask_b32_e64 v90, v90, v242, s[22:23]
	v_cndmask_b32_e64 v245, v242, v244, s[22:23]
	v_min_i32_e32 v91, v91, v245
	v_add_u32_e32 v242, v243, v246
	v_cmp_lt_i32_e64 s[22:23], v242, v240
	v_addc_co_u32_e64 v241, s[26:27], 0, v241, s[16:17]
	v_cndmask_b32_e64 v90, v90, v243, s[16:17]
	v_cndmask_b32_e64 v245, v243, v244, s[16:17]
	v_min_i32_e32 v91, v91, v245
	s_waitcnt lgkmcnt(0)
	v_add_u32_e32 v243, v242, v253
	v_cmp_lt_i32_e64 s[16:17], v243, v240
	v_addc_co_u32_e64 v241, s[26:27], 0, v241, s[22:23]
	v_cndmask_b32_e64 v90, v90, v242, s[22:23]
	v_cndmask_b32_e64 v245, v242, v244, s[22:23]
	v_min_i32_e32 v91, v91, v245
	v_add_u32_e32 v242, v243, v252
	v_cmp_lt_i32_e64 s[22:23], v242, v240
	v_addc_co_u32_e64 v241, s[26:27], 0, v241, s[16:17]
	v_cndmask_b32_e64 v90, v90, v243, s[16:17]
	v_cndmask_b32_e64 v245, v243, v244, s[16:17]
	v_min_i32_e32 v91, v91, v245
	v_add_u32_e32 v243, v242, v251
	v_cmp_lt_i32_e64 s[16:17], v243, v240
	v_addc_co_u32_e64 v241, s[26:27], 0, v241, s[22:23]
	v_cndmask_b32_e64 v90, v90, v242, s[22:23]
	v_cndmask_b32_e64 v245, v242, v244, s[22:23]
	v_min_i32_e32 v91, v91, v245
	v_add_u32_e32 v242, v243, v250
	v_cmp_lt_i32_e64 s[22:23], v242, v240
	v_addc_co_u32_e64 v241, s[26:27], 0, v241, s[16:17]
	v_cndmask_b32_e64 v90, v90, v243, s[16:17]
	v_cndmask_b32_e64 v245, v243, v244, s[16:17]
	v_min_i32_e32 v91, v91, v245
	s_nop 1
	v_addc_co_u32_e64 v241, s[26:27], 0, v241, s[22:23]
	v_cndmask_b32_e64 v90, v90, v242, s[22:23]
	v_cndmask_b32_e64 v245, v242, v244, s[22:23]
	v_min_i32_e32 v91, v91, v245
	v_sub_u32_e32 v91, v91, v90
	v_sub_u32_e32 v90, v240, v90
	v_sub_u32_e32 v241, v112, v241
	s_branch .LBB0_676
